# counted lgkmcnt waits also in the K-split unit K-loop
# speedup vs baseline: 1.0052x; 1.0052x over previous
.LBB0_794:
	s_add_i32 vcc_lo, s36, 2
	s_add_u32 s50, s34, 0x80
	s_addc_u32 s37, s35, 0
	s_add_i32 vcc_hi, 0, 0x10000
	v_add_u32_e32 v138, vcc_hi, v141
	ds_read_b128 v[162:165], v138
	ds_read_b128 v[166:169], v138 offset:1024
	ds_read_b128 v[170:173], v138 offset:2048
	ds_read_b128 v[174:177], v138 offset:3072
	s_cmp_eq_u32 s74, s36
	s_cselect_b32 s36, s30, s50
	s_cselect_b32 s37, s31, s37
	s_cselect_b32 s51, s5, s95
	s_cselect_b32 s50, s4, s94
	v_lshl_add_u64 v[138:139], s[34:35], 0, v[134:135]
	s_add_i32 m0, s66, 0xc000
	ds_read_b128 v[178:181], v143
	ds_read_b128 v[194:197], v143 offset:1024
	ds_read_b128 v[198:201], v143 offset:2048
	ds_read_b128 v[202:205], v143 offset:3072
	ds_read_b128 v[206:209], v143 offset:4096
	ds_read_b128 v[210:213], v143 offset:5120
	ds_read_b128 v[214:217], v143 offset:6144
	ds_read_b128 v[218:221], v143 offset:7168
	global_load_lds_dwordx4 v[138:139], off
	v_lshl_add_u64 v[138:139], s[34:35], 0, v[136:137]
	s_add_i32 m0, s66, 0xe000
	s_nop 0
	global_load_lds_dwordx4 v[138:139], off
	s_waitcnt lgkmcnt(8)
	s_barrier
	s_setprio 1
	s_waitcnt lgkmcnt(7)
	v_mfma_f32_16x16x32_bf16 v[124:127], v[162:165], v[178:181], v[124:127]
	v_mfma_f32_16x16x32_bf16 v[120:123], v[170:173], v[178:181], v[120:123]
	s_waitcnt lgkmcnt(5)
	v_mfma_f32_16x16x32_bf16 v[116:119], v[162:165], v[198:201], v[116:119]
	v_mfma_f32_16x16x32_bf16 v[108:111], v[170:173], v[198:201], v[108:111]
	s_waitcnt lgkmcnt(3)
	v_mfma_f32_16x16x32_bf16 v[100:103], v[162:165], v[206:209], v[100:103]
	v_mfma_f32_16x16x32_bf16 v[92:95], v[170:173], v[206:209], v[92:95]
	s_waitcnt lgkmcnt(1)
	v_mfma_f32_16x16x32_bf16 v[84:87], v[162:165], v[214:217], v[84:87]
	v_mfma_f32_16x16x32_bf16 v[76:79], v[170:173], v[214:217], v[76:79]
	v_mfma_f32_16x16x32_bf16 v[124:127], v[166:169], v[194:197], v[124:127]
	v_mfma_f32_16x16x32_bf16 v[120:123], v[174:177], v[194:197], v[120:123]
	v_mfma_f32_16x16x32_bf16 v[116:119], v[166:169], v[202:205], v[116:119]
	v_mfma_f32_16x16x32_bf16 v[108:111], v[174:177], v[202:205], v[108:111]
	v_mfma_f32_16x16x32_bf16 v[100:103], v[166:169], v[210:213], v[100:103]
	v_mfma_f32_16x16x32_bf16 v[92:95], v[174:177], v[210:213], v[92:95]
	s_waitcnt lgkmcnt(0)
	v_mfma_f32_16x16x32_bf16 v[84:87], v[166:169], v[218:221], v[84:87]
	v_mfma_f32_16x16x32_bf16 v[76:79], v[174:177], v[218:221], v[76:79]
	s_setprio 0
	s_barrier
	s_add_i32 s14, 0, 0x14000
	v_add_u32_e32 v138, s14, v141
	s_add_i32 s15, vcc_hi, s56
	ds_read_b128 v[222:225], v138
	ds_read_b128 v[226:229], v138 offset:1024
	ds_read_b128 v[230:233], v138 offset:2048
	ds_read_b128 v[234:237], v138 offset:3072
	v_lshl_add_u64 v[138:139], s[50:51], 0, v[144:145]
	s_mov_b32 m0, s15
	v_lshl_add_u64 v[238:239], s[50:51], 0, v[128:129]
	global_load_lds_dwordx4 v[138:139], off
	s_add_i32 m0, s15, 0x2000
	s_nop 0
	global_load_lds_dwordx4 v[238:239], off
	s_barrier
	s_setprio 1
	s_waitcnt lgkmcnt(3)
	v_mfma_f32_16x16x32_bf16 v[112:115], v[222:225], v[178:181], v[112:115]
	s_waitcnt lgkmcnt(1)
	v_mfma_f32_16x16x32_bf16 v[104:107], v[230:233], v[178:181], v[104:107]
	v_mfma_f32_16x16x32_bf16 v[96:99], v[222:225], v[198:201], v[96:99]
	v_mfma_f32_16x16x32_bf16 v[88:91], v[230:233], v[198:201], v[88:91]
	v_mfma_f32_16x16x32_bf16 v[80:83], v[222:225], v[206:209], v[80:83]
	v_mfma_f32_16x16x32_bf16 v[72:75], v[230:233], v[206:209], v[72:75]
	v_mfma_f32_16x16x32_bf16 v[68:71], v[222:225], v[214:217], v[68:71]
	v_mfma_f32_16x16x32_bf16 v[64:67], v[230:233], v[214:217], v[64:67]
	v_mfma_f32_16x16x32_bf16 v[112:115], v[226:229], v[194:197], v[112:115]
	s_waitcnt lgkmcnt(0)
	v_mfma_f32_16x16x32_bf16 v[104:107], v[234:237], v[194:197], v[104:107]
	v_mfma_f32_16x16x32_bf16 v[96:99], v[226:229], v[202:205], v[96:99]
	v_mfma_f32_16x16x32_bf16 v[88:91], v[234:237], v[202:205], v[88:91]
	v_mfma_f32_16x16x32_bf16 v[80:83], v[226:229], v[210:213], v[80:83]
	v_mfma_f32_16x16x32_bf16 v[72:75], v[234:237], v[210:213], v[72:75]
	v_mfma_f32_16x16x32_bf16 v[68:71], v[226:229], v[218:221], v[68:71]
	v_mfma_f32_16x16x32_bf16 v[64:67], v[234:237], v[218:221], v[64:67]
	s_setprio 0
	s_mov_b32 m0, s66
	v_lshl_add_u64 v[240:241], s[36:37], 0, v[132:133]
	s_barrier
	ds_read_b128 v[178:181], v143 offset:16384
	ds_read_b128 v[194:197], v143 offset:17408
	ds_read_b128 v[198:201], v143 offset:18432
	ds_read_b128 v[202:205], v143 offset:19456
	ds_read_b128 v[206:209], v143 offset:20480
	ds_read_b128 v[210:213], v143 offset:21504
	ds_read_b128 v[214:217], v143 offset:22528
	ds_read_b128 v[218:221], v143 offset:23552
	global_load_lds_dwordx4 v[240:241], off
	v_lshl_add_u64 v[242:243], s[36:37], 0, v[130:131]
	s_mov_b32 m0, s67
	s_nop 0
	global_load_lds_dwordx4 v[242:243], off
	s_barrier
	s_setprio 1
	s_waitcnt lgkmcnt(7)
	v_mfma_f32_16x16x32_bf16 v[60:63], v[162:165], v[178:181], v[60:63]
	v_mfma_f32_16x16x32_bf16 v[56:59], v[170:173], v[178:181], v[56:59]
	s_waitcnt lgkmcnt(5)
	v_mfma_f32_16x16x32_bf16 v[52:55], v[162:165], v[198:201], v[52:55]
	v_mfma_f32_16x16x32_bf16 v[48:51], v[170:173], v[198:201], v[48:51]
	s_waitcnt lgkmcnt(3)
	v_mfma_f32_16x16x32_bf16 v[36:39], v[162:165], v[206:209], v[36:39]
	v_mfma_f32_16x16x32_bf16 v[32:35], v[170:173], v[206:209], v[32:35]
	s_waitcnt lgkmcnt(1)
	v_mfma_f32_16x16x32_bf16 v[20:23], v[162:165], v[214:217], v[20:23]
	v_mfma_f32_16x16x32_bf16 v[16:19], v[170:173], v[214:217], v[16:19]
	v_mfma_f32_16x16x32_bf16 v[60:63], v[166:169], v[194:197], v[60:63]
	v_mfma_f32_16x16x32_bf16 v[56:59], v[174:177], v[194:197], v[56:59]
	v_mfma_f32_16x16x32_bf16 v[52:55], v[166:169], v[202:205], v[52:55]
	v_mfma_f32_16x16x32_bf16 v[48:51], v[174:177], v[202:205], v[48:51]
	v_mfma_f32_16x16x32_bf16 v[36:39], v[166:169], v[210:213], v[36:39]
	v_mfma_f32_16x16x32_bf16 v[32:35], v[174:177], v[210:213], v[32:35]
	s_waitcnt lgkmcnt(0)
	v_mfma_f32_16x16x32_bf16 v[20:23], v[166:169], v[218:221], v[20:23]
	v_mfma_f32_16x16x32_bf16 v[16:19], v[174:177], v[218:221], v[16:19]
	s_setprio 0
	s_barrier
	s_add_u32 s50, s50, s76
	s_addc_u32 s51, s51, 0
	s_add_i32 s14, s14, s56
	v_lshl_add_u64 v[244:245], s[50:51], 0, v[144:145]
	s_mov_b32 m0, s14
	v_lshl_add_u64 v[246:247], s[50:51], 0, v[128:129]
	global_load_lds_dwordx4 v[244:245], off
	s_add_i32 m0, s14, 0x2000
	s_nop 0
	global_load_lds_dwordx4 v[246:247], off
	s_waitcnt vmcnt(6)
	s_barrier
	s_setprio 1
	v_mfma_f32_16x16x32_bf16 v[44:47], v[222:225], v[178:181], v[44:47]
	v_mfma_f32_16x16x32_bf16 v[40:43], v[230:233], v[178:181], v[40:43]
	v_mfma_f32_16x16x32_bf16 v[28:31], v[222:225], v[198:201], v[28:31]
	v_mfma_f32_16x16x32_bf16 v[24:27], v[230:233], v[198:201], v[24:27]
	v_mfma_f32_16x16x32_bf16 v[12:15], v[222:225], v[206:209], v[12:15]
	v_mfma_f32_16x16x32_bf16 v[8:11], v[230:233], v[206:209], v[8:11]
	v_mfma_f32_16x16x32_bf16 v[4:7], v[222:225], v[214:217], v[4:7]
	v_mfma_f32_16x16x32_bf16 v[0:3], v[230:233], v[214:217], v[0:3]
	v_mfma_f32_16x16x32_bf16 v[44:47], v[226:229], v[194:197], v[44:47]
	v_mfma_f32_16x16x32_bf16 v[40:43], v[234:237], v[194:197], v[40:43]
	v_mfma_f32_16x16x32_bf16 v[28:31], v[226:229], v[202:205], v[28:31]
	v_mfma_f32_16x16x32_bf16 v[24:27], v[234:237], v[202:205], v[24:27]
	v_mfma_f32_16x16x32_bf16 v[12:15], v[226:229], v[210:213], v[12:15]
	v_mfma_f32_16x16x32_bf16 v[8:11], v[234:237], v[210:213], v[8:11]
	v_mfma_f32_16x16x32_bf16 v[4:7], v[226:229], v[218:221], v[4:7]
	v_mfma_f32_16x16x32_bf16 v[0:3], v[234:237], v[218:221], v[0:3]
	s_setprio 0
	s_add_i32 s14, 0, 0x18000
	v_add_u32_e32 v174, s14, v141
	s_barrier
	ds_read_b128 v[162:165], v174
	ds_read_b128 v[166:169], v174 offset:1024
	ds_read_b128 v[170:173], v174 offset:2048
	ds_read_b128 v[174:177], v174 offset:3072
	s_add_u32 s36, s36, s76
	s_addc_u32 s37, s37, 0
	s_mov_b32 m0, s70
	v_lshl_add_u64 v[222:223], s[36:37], 0, v[132:133]
	ds_read_b128 v[178:181], v143 offset:32768
	ds_read_b128 v[194:197], v143 offset:33792
	ds_read_b128 v[198:201], v143 offset:34816
	ds_read_b128 v[202:205], v143 offset:35840
	ds_read_b128 v[206:209], v143 offset:36864
	ds_read_b128 v[210:213], v143 offset:37888
	ds_read_b128 v[214:217], v143 offset:38912
	ds_read_b128 v[218:221], v143 offset:39936
	global_load_lds_dwordx4 v[222:223], off
	v_lshl_add_u64 v[222:223], s[36:37], 0, v[130:131]
	s_mov_b32 m0, s71
	s_nop 0
	global_load_lds_dwordx4 v[222:223], off
	s_waitcnt lgkmcnt(8)
	s_barrier
	s_setprio 1
	s_waitcnt lgkmcnt(7)
	v_mfma_f32_16x16x32_bf16 v[124:127], v[162:165], v[178:181], v[124:127]
	v_mfma_f32_16x16x32_bf16 v[120:123], v[170:173], v[178:181], v[120:123]
	s_waitcnt lgkmcnt(5)
	v_mfma_f32_16x16x32_bf16 v[116:119], v[162:165], v[198:201], v[116:119]
	v_mfma_f32_16x16x32_bf16 v[108:111], v[170:173], v[198:201], v[108:111]
	s_waitcnt lgkmcnt(3)
	v_mfma_f32_16x16x32_bf16 v[100:103], v[162:165], v[206:209], v[100:103]
	v_mfma_f32_16x16x32_bf16 v[92:95], v[170:173], v[206:209], v[92:95]
	s_waitcnt lgkmcnt(1)
	v_mfma_f32_16x16x32_bf16 v[84:87], v[162:165], v[214:217], v[84:87]
	v_mfma_f32_16x16x32_bf16 v[76:79], v[170:173], v[214:217], v[76:79]
	v_mfma_f32_16x16x32_bf16 v[124:127], v[166:169], v[194:197], v[124:127]
	v_mfma_f32_16x16x32_bf16 v[120:123], v[174:177], v[194:197], v[120:123]
	v_mfma_f32_16x16x32_bf16 v[116:119], v[166:169], v[202:205], v[116:119]
	v_mfma_f32_16x16x32_bf16 v[108:111], v[174:177], v[202:205], v[108:111]
	v_mfma_f32_16x16x32_bf16 v[100:103], v[166:169], v[210:213], v[100:103]
	v_mfma_f32_16x16x32_bf16 v[92:95], v[174:177], v[210:213], v[92:95]
	s_waitcnt lgkmcnt(0)
	v_mfma_f32_16x16x32_bf16 v[84:87], v[166:169], v[218:221], v[84:87]
	v_mfma_f32_16x16x32_bf16 v[76:79], v[174:177], v[218:221], v[76:79]
	s_setprio 0
	s_barrier
	s_add_i32 s15, 0, 0x1c000
	s_add_i32 s14, s14, s56
	v_add_u32_e32 v193, s15, v141
	v_lshl_add_u64 v[138:139], v[138:139], 0, s[86:87]
	s_mov_b32 m0, s14
	ds_read_b128 v[222:225], v193
	ds_read_b128 v[226:229], v193 offset:1024
	ds_read_b128 v[230:233], v193 offset:2048
	ds_read_b128 v[234:237], v193 offset:3072
	global_load_lds_dwordx4 v[138:139], off
	v_lshl_add_u64 v[138:139], v[238:239], 0, s[86:87]
	s_add_i32 m0, s14, 0x2000
	s_nop 0
	global_load_lds_dwordx4 v[138:139], off
	s_barrier
	s_setprio 1
	s_waitcnt lgkmcnt(3)
	v_mfma_f32_16x16x32_bf16 v[112:115], v[222:225], v[178:181], v[112:115]
	s_waitcnt lgkmcnt(1)
	v_mfma_f32_16x16x32_bf16 v[104:107], v[230:233], v[178:181], v[104:107]
	v_mfma_f32_16x16x32_bf16 v[96:99], v[222:225], v[198:201], v[96:99]
	v_mfma_f32_16x16x32_bf16 v[88:91], v[230:233], v[198:201], v[88:91]
	v_mfma_f32_16x16x32_bf16 v[80:83], v[222:225], v[206:209], v[80:83]
	v_mfma_f32_16x16x32_bf16 v[72:75], v[230:233], v[206:209], v[72:75]
	v_mfma_f32_16x16x32_bf16 v[68:71], v[222:225], v[214:217], v[68:71]
	v_mfma_f32_16x16x32_bf16 v[64:67], v[230:233], v[214:217], v[64:67]
	v_mfma_f32_16x16x32_bf16 v[112:115], v[226:229], v[194:197], v[112:115]
	s_waitcnt lgkmcnt(0)
	v_mfma_f32_16x16x32_bf16 v[104:107], v[234:237], v[194:197], v[104:107]
	v_mfma_f32_16x16x32_bf16 v[96:99], v[226:229], v[202:205], v[96:99]
	v_mfma_f32_16x16x32_bf16 v[88:91], v[234:237], v[202:205], v[88:91]
	v_mfma_f32_16x16x32_bf16 v[80:83], v[226:229], v[210:213], v[80:83]
	v_mfma_f32_16x16x32_bf16 v[72:75], v[234:237], v[210:213], v[72:75]
	v_mfma_f32_16x16x32_bf16 v[68:71], v[226:229], v[218:221], v[68:71]
	v_mfma_f32_16x16x32_bf16 v[64:67], v[234:237], v[218:221], v[64:67]
	s_setprio 0
	s_mov_b32 m0, s72
	v_lshl_add_u64 v[138:139], v[240:241], 0, s[86:87]
	s_barrier
	ds_read_b128 v[178:181], v143 offset:49152
	ds_read_b128 v[194:197], v143 offset:50176
	ds_read_b128 v[198:201], v143 offset:51200
	ds_read_b128 v[202:205], v143 offset:52224
	ds_read_b128 v[206:209], v143 offset:53248
	ds_read_b128 v[210:213], v143 offset:54272
	ds_read_b128 v[214:217], v143 offset:55296
	ds_read_b128 v[218:221], v143 offset:56320
	global_load_lds_dwordx4 v[138:139], off
	v_lshl_add_u64 v[138:139], v[242:243], 0, s[86:87]
	s_mov_b32 m0, s73
	s_nop 0
	global_load_lds_dwordx4 v[138:139], off
	s_barrier
	s_setprio 1
	s_waitcnt lgkmcnt(7)
	v_mfma_f32_16x16x32_bf16 v[60:63], v[162:165], v[178:181], v[60:63]
	v_mfma_f32_16x16x32_bf16 v[56:59], v[170:173], v[178:181], v[56:59]
	s_waitcnt lgkmcnt(5)
	v_mfma_f32_16x16x32_bf16 v[52:55], v[162:165], v[198:201], v[52:55]
	v_mfma_f32_16x16x32_bf16 v[48:51], v[170:173], v[198:201], v[48:51]
	s_waitcnt lgkmcnt(3)
	v_mfma_f32_16x16x32_bf16 v[36:39], v[162:165], v[206:209], v[36:39]
	v_mfma_f32_16x16x32_bf16 v[32:35], v[170:173], v[206:209], v[32:35]
	s_waitcnt lgkmcnt(1)
	v_mfma_f32_16x16x32_bf16 v[20:23], v[162:165], v[214:217], v[20:23]
	v_mfma_f32_16x16x32_bf16 v[16:19], v[170:173], v[214:217], v[16:19]
	v_mfma_f32_16x16x32_bf16 v[60:63], v[166:169], v[194:197], v[60:63]
	v_mfma_f32_16x16x32_bf16 v[56:59], v[174:177], v[194:197], v[56:59]
	v_mfma_f32_16x16x32_bf16 v[52:55], v[166:169], v[202:205], v[52:55]
	v_mfma_f32_16x16x32_bf16 v[48:51], v[174:177], v[202:205], v[48:51]
	v_mfma_f32_16x16x32_bf16 v[36:39], v[166:169], v[210:213], v[36:39]
	v_mfma_f32_16x16x32_bf16 v[32:35], v[174:177], v[210:213], v[32:35]
	s_waitcnt lgkmcnt(0)
	v_mfma_f32_16x16x32_bf16 v[20:23], v[166:169], v[218:221], v[20:23]
	v_mfma_f32_16x16x32_bf16 v[16:19], v[174:177], v[218:221], v[16:19]
	s_setprio 0
	s_barrier
	s_add_i32 s14, s15, s56
	v_lshl_add_u64 v[138:139], v[244:245], 0, s[86:87]
	s_mov_b32 m0, s14
	s_nop 0
	global_load_lds_dwordx4 v[138:139], off
	v_lshl_add_u64 v[138:139], v[246:247], 0, s[86:87]
	s_add_i32 m0, s14, 0x2000
	s_nop 0
	global_load_lds_dwordx4 v[138:139], off
	s_waitcnt vmcnt(6)
	s_barrier
	s_setprio 1
	v_mfma_f32_16x16x32_bf16 v[44:47], v[222:225], v[178:181], v[44:47]
	v_mfma_f32_16x16x32_bf16 v[40:43], v[230:233], v[178:181], v[40:43]
	v_mfma_f32_16x16x32_bf16 v[28:31], v[222:225], v[198:201], v[28:31]
	v_mfma_f32_16x16x32_bf16 v[24:27], v[230:233], v[198:201], v[24:27]
	v_mfma_f32_16x16x32_bf16 v[12:15], v[222:225], v[206:209], v[12:15]
	v_mfma_f32_16x16x32_bf16 v[8:11], v[230:233], v[206:209], v[8:11]
	v_mfma_f32_16x16x32_bf16 v[4:7], v[222:225], v[214:217], v[4:7]
	v_mfma_f32_16x16x32_bf16 v[0:3], v[230:233], v[214:217], v[0:3]
	v_mfma_f32_16x16x32_bf16 v[44:47], v[226:229], v[194:197], v[44:47]
	v_mfma_f32_16x16x32_bf16 v[40:43], v[234:237], v[194:197], v[40:43]
	v_mfma_f32_16x16x32_bf16 v[28:31], v[226:229], v[202:205], v[28:31]
	v_mfma_f32_16x16x32_bf16 v[24:27], v[234:237], v[202:205], v[24:27]
	v_mfma_f32_16x16x32_bf16 v[12:15], v[226:229], v[210:213], v[12:15]
	v_mfma_f32_16x16x32_bf16 v[8:11], v[234:237], v[210:213], v[8:11]
	v_mfma_f32_16x16x32_bf16 v[4:7], v[226:229], v[218:221], v[4:7]
	v_mfma_f32_16x16x32_bf16 v[0:3], v[234:237], v[218:221], v[0:3]
	s_setprio 0
	s_add_u32 s34, s34, 0x100
	s_addc_u32 s35, s35, 0
	s_add_u32 s94, s94, 0x100
	s_addc_u32 s95, s95, 0
	s_cmp_ge_u32 vcc_lo, s12
	s_mov_b32 s36, vcc_lo
	s_barrier
	s_cbranch_scc0 .LBB0_794
	s_ashr_i32 s34, s88, 31
	s_lshr_b32 s34, s34, 29
	s_add_i32 s34, s88, s34
	s_ashr_i32 s94, s34, 3
	s_lshl_b32 s34, s94, 21
	s_add_u32 s36, s16, s34
	s_addc_u32 s37, s17, 0
	s_branch .LBB0_782
